# G0 K-loop back-edge rotation (7.11): next iteration's scalar preamble computed before the loop-end barrier
# baseline (speedup 1.0000x reference)
; DI f32x4 mfma16(bf16x8 a, bf16x8 b, f32x4 c) { return __builtin_amdgcn_mfma_f32_16x16x32_bf16(a, b, c, 0, 0, 0); }
; DI void tile_coords(int t, int NTN, int& m0, int& n0) {
;   const int panel = t / (8 * NTN), within = t % (8 * NTN);
;   int tm, tn;
;   if (panel < 16) { tn = within >> 3; tm = panel * 8 + (within & 7); } else { tm = 128; tn = t - 16 * 8 * NTN; }
;   m0 = tm * 128; n0 = tn * 128;
; }
; template <int MODE>
; PH void gemm_phase(const Params& p, int layer) {
;     ...
;           for (int ks = 0; ks < 2; ++ks) {
;             bf16x8 wf[4], xf[4];
; #pragma unroll
;             for (int i = 0; i < 4; ++i) {
;               wf[i] = ldfrag(cW, 72, wn * 64 + i * 16, ks * 32, lane);
;               xf[i] = ldfrag(cX, 72, wm * 64 + i * 16, ks * 32, lane);
;             }
;             __builtin_amdgcn_sched_barrier(0);
; #pragma unroll
;             for (int nt = 0; nt < 4; ++nt) {
; #pragma unroll
;               for (int mt = 0; mt < 4; ++mt) acc[nt][mt] = mfma16(wf[nt], xf[mt], acc[nt][mt]);
;               if (ks == 0) *(u32x4*)(dX + soff + nt * 32 * 72) = rx[(s + 1) & 1][nt];
;               else         *(u32x4*)(dW + soff + nt * 32 * 72) = rw[(s + 1) & 1][nt];
;               __builtin_amdgcn_sched_barrier(0);
;             }
;             if (ks == 0) { GLOAD(s, g + 2); __builtin_amdgcn_sched_barrier(0); }
.Lg0rot_head:
	s_waitcnt vmcnt(9)
	ds_read_b128 v[96:99], v233 offset:36864
	s_waitcnt vmcnt(7)
	ds_read_b128 v[100:103], v233 offset:38912
	s_waitcnt vmcnt(3)
	ds_read_b128 v[104:107], v234
	ds_read_b128 v[108:111], v234 offset:2048
	s_waitcnt vmcnt(1)
	ds_read_b128 v[112:115], v233 offset:40960
	ds_read_b128 v[116:119], v233 offset:43008
	ds_read_b128 v[120:123], v234 offset:4096
	ds_read_b128 v[124:127], v234 offset:6144
	s_add_i32 s6, s6, s44
	s_mul_hi_i32 s22, s6, 0xd20d20d3
	s_add_i32 s22, s22, s6
	s_lshr_b32 s42, s22, 31
	s_ashr_i32 s22, s22, 8
	s_add_i32 s22, s22, s42
	s_mul_i32 s42, s22, 0x138
	s_sub_i32 s42, s6, s42
	s_lshr_b32 s43, s42, 3
	s_lshl_b32 s42, s42, 7
	s_lshl_b32 s22, s22, 10
	s_and_b32 s42, s42, 0x380
	s_lshl_b32 s2, s2, 7
	s_add_i32 s7, s6, 0xffffec80
	s_or_b32 s22, s42, s22
	s_and_b32 s2, s2, 0x780
	s_cmpk_lt_i32 s6, 0x1380
	s_cselect_b32 s76, s22, 0x4000
	s_cselect_b32 s78, s43, s7
	s_lshl_b32 s76, s76, 11
	s_lshl_b32 s78, s78, 18
	s_add_i32 s76, s76, s2
	s_add_i32 s78, s78, s2
	s_add_u32 s76, s72, s76
	s_addc_u32 s77, s73, 0
	s_add_u32 s78, s74, s78
	s_addc_u32 s79, s75, 0
	s_waitcnt lgkmcnt(5)
	v_mfma_f32_16x16x32_bf16 v[92:95], v[96:99], v[104:107], v[92:95]
	s_waitcnt vmcnt(7)
	ds_write_b128 v203, v[16:19] offset:18432
	s_waitcnt lgkmcnt(5)
	v_mfma_f32_16x16x32_bf16 v[88:91], v[96:99], v[108:111], v[88:91]
	s_waitcnt lgkmcnt(2)
	v_mfma_f32_16x16x32_bf16 v[84:87], v[96:99], v[120:123], v[84:87]
	s_waitcnt lgkmcnt(1)
	v_mfma_f32_16x16x32_bf16 v[16:19], v[96:99], v[124:127], v[80:83]
	v_mfma_f32_16x16x32_bf16 v[76:79], v[100:103], v[104:107], v[76:79]
	s_waitcnt vmcnt(5)
	ds_write_b128 v203, v[20:23] offset:22528
	v_mfma_f32_16x16x32_bf16 v[72:75], v[100:103], v[108:111], v[72:75]
	v_mfma_f32_16x16x32_bf16 v[68:71], v[100:103], v[120:123], v[68:71]
	v_mfma_f32_16x16x32_bf16 v[20:23], v[100:103], v[124:127], v[64:67]
	v_mfma_f32_16x16x32_bf16 v[60:63], v[112:115], v[104:107], v[60:63]
	s_waitcnt vmcnt(3)
	ds_write_b128 v203, v[24:27] offset:26624
	v_mfma_f32_16x16x32_bf16 v[56:59], v[112:115], v[108:111], v[56:59]
	v_mfma_f32_16x16x32_bf16 v[52:55], v[112:115], v[120:123], v[52:55]
	v_mfma_f32_16x16x32_bf16 v[24:27], v[112:115], v[124:127], v[48:51]
	v_mfma_f32_16x16x32_bf16 v[44:47], v[116:119], v[104:107], v[44:47]
	s_waitcnt vmcnt(1)
	ds_write_b128 v203, v[28:31] offset:30720
	v_mfma_f32_16x16x32_bf16 v[40:43], v[116:119], v[108:111], v[40:43]
	v_mfma_f32_16x16x32_bf16 v[36:39], v[116:119], v[120:123], v[36:39]
	v_mfma_f32_16x16x32_bf16 v[28:31], v[116:119], v[124:127], v[32:35]
	ds_read_b128 v[112:115], v240 offset:36864
	ds_read_b128 v[116:119], v240 offset:38912
	ds_read_b128 v[120:123], v241
	ds_read_b128 v[124:127], v241 offset:2048
	ds_read_b128 v[128:131], v240 offset:40960
	s_waitcnt vmcnt(8)
	ds_read_b128 v[132:135], v240 offset:43008
	ds_read_b128 v[136:139], v241 offset:4096
	ds_read_b128 v[146:149], v241 offset:6144
	global_load_dwordx4 v[32:35], v242, s[76:77]
	global_load_dwordx4 v[48:51], v242, s[78:79]
	global_load_dwordx4 v[64:67], v243, s[76:77]
	global_load_dwordx4 v[96:99], v243, s[78:79]
	global_load_dwordx4 v[80:83], v244, s[76:77]
	global_load_dwordx4 v[100:103], v244, s[78:79]
	global_load_dwordx4 v[104:107], v245, s[76:77]
	global_load_dwordx4 v[108:111], v245, s[78:79]
	s_waitcnt lgkmcnt(5)
	v_mfma_f32_16x16x32_bf16 v[92:95], v[112:115], v[120:123], v[92:95]
	ds_write_b128 v203, v[0:3] offset:55296
	s_waitcnt lgkmcnt(5)
	v_mfma_f32_16x16x32_bf16 v[88:91], v[112:115], v[124:127], v[88:91]
	s_waitcnt lgkmcnt(2)
	v_mfma_f32_16x16x32_bf16 v[84:87], v[112:115], v[136:139], v[84:87]
	s_waitcnt lgkmcnt(1)
	v_mfma_f32_16x16x32_bf16 v[0:3], v[112:115], v[146:149], v[16:19]
	v_mfma_f32_16x16x32_bf16 v[16:19], v[116:119], v[120:123], v[76:79]
	ds_write_b128 v203, v[4:7] offset:59392
	v_mfma_f32_16x16x32_bf16 v[72:75], v[116:119], v[124:127], v[72:75]
	v_mfma_f32_16x16x32_bf16 v[68:71], v[116:119], v[136:139], v[68:71]
	v_mfma_f32_16x16x32_bf16 v[4:7], v[116:119], v[146:149], v[20:23]
	v_mfma_f32_16x16x32_bf16 v[20:23], v[128:131], v[120:123], v[60:63]
	ds_write_b128 v203, v[8:11] offset:63488
	v_mfma_f32_16x16x32_bf16 v[56:59], v[128:131], v[124:127], v[56:59]
	v_mfma_f32_16x16x32_bf16 v[52:55], v[128:131], v[136:139], v[52:55]
	v_mfma_f32_16x16x32_bf16 v[8:11], v[128:131], v[146:149], v[24:27]
	v_mfma_f32_16x16x32_bf16 v[24:27], v[132:135], v[120:123], v[44:47]
	s_waitcnt vmcnt(8)
	ds_write_b128 v204, v[12:15] offset:30720
	v_mfma_f32_16x16x32_bf16 v[40:43], v[132:135], v[124:127], v[40:43]
	v_mfma_f32_16x16x32_bf16 v[36:39], v[132:135], v[136:139], v[36:39]
	v_mfma_f32_16x16x32_bf16 v[12:15], v[132:135], v[146:149], v[28:31]
	s_min_i32 s2, s25, s45
	s_ashr_i32 s6, s2, 4
	s_waitcnt lgkmcnt(0)
	s_barrier
; template <int MODE>
; PH void gemm_phase(const Params& p, int layer) {
;     ...
;     for (int g0 = 0; g0 < total; g0 += 2) {
; #pragma unroll
;       for (int s = 0; s < 2; ++s) {
;         const int g = g0 + s;
;         {
;           const int kt = g & (NK - 1), it = g >> LOGNK;
;           if (kt == 0) {
; #pragma unroll
;             for (int a = 0; a < 4; ++a)
; #pragma unroll
;               for (int b = 0; b < 4; ++b) acc[a][b] = (f32x4){0.f, 0.f, 0.f, 0.f};
;           }
;           if (MODE == 1 && kt == 12) {
;             int m0, n0; tile_coords(it * G + off, NTN, m0, n0);
;             const float* SSQ = (const float*)(p.ws + WS_SSQ);
; #pragma unroll
;             for (int mt = 0; mt < 4; ++mt) {
;               const int m = m0 + wm * 64 + mt * 16 + l15;
;               const float4 s0 = *(const float4*)(SSQ + (size_t)m * 12), s1 = *(const float4*)(SSQ + (size_t)m * 12 + 4), s2 = *(const float4*)(SSQ + (size_t)m * 12 + 8);
;               const float ss = s0.x + s0.y + s0.z + s0.w + s1.x + s1.y + s1.z + s1.w + s2.x + s2.y + s2.z + s2.w;
;               const float rs = rsqrtf(ss * (1.f / 768.f) + 1e-5f);
; #pragma unroll
;               for (int nt = 0; nt < 4; ++nt) acc[nt][mt] *= rs;
;             }
;           }
;           const u16* cX = sX + (g & 1) * 128 * 72;
;           const u16* cW = sW + (g & 1) * 128 * 72;
;           u16* dX = sX + ((g + 1) & 1) * 128 * 72;
;           u16* dW = sW + ((g + 1) & 1) * 128 * 72;
; #pragma unroll
;           for (int ks = 0; ks < 2; ++ks) {
;             bf16x8 wf[4], xf[4];
; #pragma unroll
;             for (int i = 0; i < 4; ++i) {
;               wf[i] = ldfrag(cW, 72, wn * 64 + i * 16, ks * 32, lane);
;               xf[i] = ldfrag(cX, 72, wm * 64 + i * 16, ks * 32, lane);
;             }
;             __builtin_amdgcn_sched_barrier(0);
; #pragma unroll
;             for (int nt = 0; nt < 4; ++nt) {
; #pragma unroll
;               for (int mt = 0; mt < 4; ++mt) acc[nt][mt] = mfma16(wf[nt], xf[mt], acc[nt][mt]);
;               if (ks == 0) *(u32x4*)(dX + soff + nt * 32 * 72) = rx[(s + 1) & 1][nt];
;               else         *(u32x4*)(dW + soff + nt * 32 * 72) = rw[(s + 1) & 1][nt];
;               __builtin_amdgcn_sched_barrier(0);
;             }
;             if (ks == 0) { GLOAD(s, g + 2); __builtin_amdgcn_sched_barrier(0); }
;           }
;           __syncthreads();
	s_mul_i32 s6, s6, s64
	ds_read_b128 v[28:31], v233 offset:55296
	ds_read_b128 v[44:47], v233 offset:57344
	ds_read_b128 v[60:63], v234 offset:18432
	ds_read_b128 v[76:79], v234 offset:20480
	ds_read_b128 v[112:115], v233 offset:59392
	ds_read_b128 v[116:119], v233 offset:61440
	ds_read_b128 v[120:123], v234 offset:22528
	ds_read_b128 v[124:127], v234 offset:24576
	s_add_i32 s6, s6, s44
	s_mul_hi_i32 s22, s6, 0xd20d20d3
	s_add_i32 s22, s22, s6
	s_lshr_b32 s42, s22, 31
	s_ashr_i32 s22, s22, 8
	s_add_i32 s22, s22, s42
	s_mul_i32 s42, s22, 0x138
	s_sub_i32 s42, s6, s42
	s_lshr_b32 s43, s42, 3
	s_lshl_b32 s42, s42, 7
	s_lshl_b32 s22, s22, 10
	s_and_b32 s42, s42, 0x380
	s_lshl_b32 s2, s2, 7
	s_add_i32 s7, s6, 0xffffec80
	s_or_b32 s22, s42, s22
	s_and_b32 s2, s2, 0x780
	s_cmpk_lt_i32 s6, 0x1380
	s_cselect_b32 s76, s22, 0x4000
	s_cselect_b32 s78, s43, s7
	s_lshl_b32 s76, s76, 11
	s_lshl_b32 s78, s78, 18
	s_add_i32 s76, s76, s2
	s_add_i32 s78, s78, s2
	s_add_u32 s76, s72, s76
	s_addc_u32 s77, s73, 0
	s_add_u32 s78, s74, s78
	s_addc_u32 s79, s75, 0
	s_waitcnt lgkmcnt(5)
	v_mfma_f32_16x16x32_bf16 v[92:95], v[28:31], v[60:63], v[92:95]
	s_waitcnt vmcnt(7)
	ds_write_b128 v203, v[32:35]
	s_waitcnt lgkmcnt(5)
	v_mfma_f32_16x16x32_bf16 v[88:91], v[28:31], v[76:79], v[88:91]
	s_waitcnt lgkmcnt(2)
	v_mfma_f32_16x16x32_bf16 v[84:87], v[28:31], v[120:123], v[84:87]
	s_waitcnt lgkmcnt(1)
	v_mfma_f32_16x16x32_bf16 v[32:35], v[28:31], v[124:127], v[0:3]
	v_mfma_f32_16x16x32_bf16 v[128:131], v[44:47], v[60:63], v[16:19]
	s_waitcnt vmcnt(5)
	ds_write_b128 v203, v[64:67] offset:4096
	v_mfma_f32_16x16x32_bf16 v[72:75], v[44:47], v[76:79], v[72:75]
	v_mfma_f32_16x16x32_bf16 v[68:71], v[44:47], v[120:123], v[68:71]
	v_mfma_f32_16x16x32_bf16 v[44:47], v[44:47], v[124:127], v[4:7]
	v_mfma_f32_16x16x32_bf16 v[56:59], v[112:115], v[76:79], v[56:59]
	s_waitcnt vmcnt(3)
	ds_write_b128 v203, v[80:83] offset:8192
	v_mfma_f32_16x16x32_bf16 v[52:55], v[112:115], v[120:123], v[52:55]
	v_mfma_f32_16x16x32_bf16 v[132:135], v[112:115], v[60:63], v[20:23]
	v_mfma_f32_16x16x32_bf16 v[112:115], v[112:115], v[124:127], v[8:11]
	v_mfma_f32_16x16x32_bf16 v[40:43], v[116:119], v[76:79], v[40:43]
	s_waitcnt vmcnt(1)
	ds_write_b128 v203, v[104:107] offset:12288
	v_mfma_f32_16x16x32_bf16 v[36:39], v[116:119], v[120:123], v[36:39]
	v_mfma_f32_16x16x32_bf16 v[136:139], v[116:119], v[60:63], v[24:27]
	v_mfma_f32_16x16x32_bf16 v[104:107], v[116:119], v[124:127], v[12:15]
	ds_read_b128 v[60:63], v240 offset:55296
	ds_read_b128 v[64:67], v240 offset:57344
	ds_read_b128 v[116:119], v241 offset:18432
	ds_read_b128 v[120:123], v241 offset:20480
	ds_read_b128 v[124:127], v240 offset:59392
	ds_read_b128 v[146:149], v240 offset:61440
	ds_read_b128 v[150:153], v241 offset:22528
	ds_read_b128 v[154:157], v241 offset:24576
	global_load_dwordx4 v[16:19], v242, s[76:77]
	global_load_dwordx4 v[0:3], v242, s[78:79]
	global_load_dwordx4 v[20:23], v243, s[76:77]
	global_load_dwordx4 v[4:7], v243, s[78:79]
	global_load_dwordx4 v[24:27], v244, s[76:77]
	global_load_dwordx4 v[8:11], v244, s[78:79]
	global_load_dwordx4 v[28:31], v245, s[76:77]
	global_load_dwordx4 v[12:15], v245, s[78:79]
	s_waitcnt lgkmcnt(5)
	v_mfma_f32_16x16x32_bf16 v[92:95], v[60:63], v[116:119], v[92:95]
	ds_write_b128 v203, v[48:51] offset:36864
	s_waitcnt lgkmcnt(5)
	v_mfma_f32_16x16x32_bf16 v[88:91], v[60:63], v[120:123], v[88:91]
	s_waitcnt lgkmcnt(2)
	v_mfma_f32_16x16x32_bf16 v[84:87], v[60:63], v[150:153], v[84:87]
	s_waitcnt lgkmcnt(1)
	v_mfma_f32_16x16x32_bf16 v[80:83], v[60:63], v[154:157], v[32:35]
	v_mfma_f32_16x16x32_bf16 v[76:79], v[64:67], v[116:119], v[128:131]
	ds_write_b128 v203, v[96:99] offset:40960
	v_mfma_f32_16x16x32_bf16 v[72:75], v[64:67], v[120:123], v[72:75]
	v_mfma_f32_16x16x32_bf16 v[68:71], v[64:67], v[150:153], v[68:71]
	v_mfma_f32_16x16x32_bf16 v[64:67], v[64:67], v[154:157], v[44:47]
	v_mfma_f32_16x16x32_bf16 v[60:63], v[124:127], v[116:119], v[132:135]
	ds_write_b128 v203, v[100:103] offset:45056
	v_mfma_f32_16x16x32_bf16 v[56:59], v[124:127], v[120:123], v[56:59]
	v_mfma_f32_16x16x32_bf16 v[52:55], v[124:127], v[150:153], v[52:55]
	v_mfma_f32_16x16x32_bf16 v[48:51], v[124:127], v[154:157], v[112:115]
	v_mfma_f32_16x16x32_bf16 v[44:47], v[146:149], v[116:119], v[136:139]
	s_waitcnt vmcnt(8)
	ds_write_b128 v203, v[108:111] offset:49152
	v_mfma_f32_16x16x32_bf16 v[40:43], v[146:149], v[120:123], v[40:43]
	v_mfma_f32_16x16x32_bf16 v[36:39], v[146:149], v[150:153], v[36:39]
	v_mfma_f32_16x16x32_bf16 v[32:35], v[146:149], v[154:157], v[104:107]
	s_cmp_lg_u32 s1, 14
	s_cbranch_scc0 .Lg0rot_tile
	s_add_i32 s25, s25, 2
	v_readlane_b32 s0, v254, 63
	s_cmp_lt_i32 s13, s0
	s_cbranch_scc0 .Lg0rot_exit
	s_add_i32 s0, s25, -3
	s_and_b32 s1, s0, 14
	s_add_i32 s13, s25, -1
	v_readlane_b32 s45, v254, 57
	s_min_i32 s2, s13, s45
	s_ashr_i32 s6, s2, 4
	s_mul_i32 s6, s6, s64
	v_readlane_b32 s44, v255, 8
	s_waitcnt lgkmcnt(0)
	s_barrier
	s_branch .Lg0rot_head
.Lg0rot_exit:
	s_waitcnt lgkmcnt(0)
	s_barrier
	s_branch .LBB0_189
	s_nop 0
	s_nop 0
	s_nop 0
	s_nop 0
	s_nop 0
	s_nop 0
	s_nop 0
	s_nop 0
	s_nop 0
	s_nop 0
	s_nop 0
	s_nop 0
	s_nop 0
	s_nop 0
	s_nop 0
	s_nop 0
	s_nop 0
	s_nop 0
	s_nop 0
	s_nop 0
	s_nop 0
	s_nop 0
	s_nop 0
	s_nop 0
	s_nop 0
	s_nop 0
	s_nop 0
	s_nop 0
	s_nop 0
	s_nop 0
	s_nop 0
	s_nop 0
	s_nop 0
	s_nop 0
	s_nop 0
	s_nop 0
	s_nop 0
	s_nop 0
	s_nop 0
	s_nop 0
	s_nop 0
	s_nop 0
	s_nop 0
; DI unsigned pack2(float a, float b) { fl2_t v = {a, b}; return __builtin_bit_cast(unsigned, __builtin_convertvector(v, bf2_t)); }
; template <int MODE>
; PH void gemm_phase(const Params& p, int layer) {
;     ...
;           if (kt == NK - 1) {
;             int m0, n0; tile_coords(it * G + off, NTN, m0, n0);
;             if (MODE == 0) {
;               u16* PROJ = (u16*)(p.ws + WS_PROJ);
;               u16* eX = sX + (g & 1) * 128 * 72;
;               u16* eW = sW + (g & 1) * 128 * 72;
; #pragma unroll
;               for (int mt = 0; mt < 4; ++mt) {
;                 const int ml = mt * 16 + l15;
;                 u16* eb = (wm == 0 ? eX : eW) + ml * 136;
; #pragma unroll
;                 for (int nt = 0; nt < 4; ++nt) {
;                   const int nl = wn * 64 + nt * 16 + quad * 4;
;                   uint2 o; o.x = pack2(acc[nt][mt][0], acc[nt][mt][1]); o.y = pack2(acc[nt][mt][2], acc[nt][mt][3]);
;                   *(uint2*)(eb + nl) = o;
;                 }
;               }
;               __syncthreads();
; #pragma unroll
;               for (int i = 0; i < 8; ++i) {
;                 const int row = (tid >> 4) + 16 * i, ch = tid & 15;
;                 const u16* eb = (row < 64 ? eX + row * 136 : eW + (row - 64) * 136) + ch * 8;
;                 *(u32x4*)(PROJ + (size_t)(m0 + row) * NPAD + n0 + ch * 8) = *(const u32x4*)eb;
;               }
;               {
;                 const int tn_ = n0 >> 7;
;                 const bool is_lru = (tn_ >= 10) && (tn_ < 16), is_ssd = (tn_ >= 28) && (tn_ < 38);
;                 if ((is_lru || is_ssd) && m0 < MP) {
.Lg0rot_tile:
	s_waitcnt lgkmcnt(0)
	s_barrier
	s_lshr_b32 s0, s0, 4
	s_mul_i32 s0, s0, s64
	v_readlane_b32 s1, v255, 8
	s_add_i32 s0, s0, s1
	s_mul_hi_i32 s2, s0, 0xd20d20d3
	s_add_i32 s2, s2, s0
	s_lshr_b32 s6, s2, 31
	s_ashr_i32 s2, s2, 8
	v_cvt_pk_bf16_f32 v96, v92, v93
	v_cvt_pk_bf16_f32 v97, v94, v95
	v_cvt_pk_bf16_f32 v98, v76, v77
	v_cvt_pk_bf16_f32 v99, v78, v79
	s_add_i32 s2, s2, s6
	ds_write2_b64 v235, v[96:97], v[98:99] offset1:4
	v_cvt_pk_bf16_f32 v96, v60, v61
	v_cvt_pk_bf16_f32 v97, v62, v63
	v_cvt_pk_bf16_f32 v98, v44, v45
	v_cvt_pk_bf16_f32 v99, v46, v47
	s_mul_i32 s6, s2, 0x138
	ds_write2_b64 v235, v[96:97], v[98:99] offset0:8 offset1:12
	v_cvt_pk_bf16_f32 v96, v88, v89
	v_cvt_pk_bf16_f32 v97, v90, v91
	v_cvt_pk_bf16_f32 v98, v72, v73
	v_cvt_pk_bf16_f32 v99, v74, v75
	v_add_u32_e32 v100, 0x1000, v235
	s_sub_i32 s6, s0, s6
	ds_write2_b64 v100, v[96:97], v[98:99] offset0:32 offset1:36
	v_cvt_pk_bf16_f32 v96, v56, v57
	v_cvt_pk_bf16_f32 v97, v58, v59
	v_cvt_pk_bf16_f32 v98, v40, v41
	v_cvt_pk_bf16_f32 v99, v42, v43
	s_ashr_i32 s7, s6, 3
	s_lshl_b32 s6, s6, 7
	ds_write2_b64 v100, v[96:97], v[98:99] offset0:40 offset1:44
	v_cvt_pk_bf16_f32 v96, v84, v85
	v_cvt_pk_bf16_f32 v97, v86, v87
	v_cvt_pk_bf16_f32 v98, v68, v69
	v_cvt_pk_bf16_f32 v99, v70, v71
	v_add_u32_e32 v100, 0x2000, v235
	s_lshl_b32 s2, s2, 10
	s_and_b32 s6, s6, 0x380
	ds_write2_b64 v100, v[96:97], v[98:99] offset0:64 offset1:68
	v_cvt_pk_bf16_f32 v96, v52, v53
	v_cvt_pk_bf16_f32 v97, v54, v55
	v_cvt_pk_bf16_f32 v98, v36, v37
	v_cvt_pk_bf16_f32 v99, v38, v39
	s_add_i32 s1, s0, 0xffffec80
	s_or_b32 s2, s6, s2
	ds_write2_b64 v100, v[96:97], v[98:99] offset0:72 offset1:76
	v_cvt_pk_bf16_f32 v96, v80, v81
	v_cvt_pk_bf16_f32 v97, v82, v83
	v_cvt_pk_bf16_f32 v98, v64, v65
	v_cvt_pk_bf16_f32 v99, v66, v67
	v_add_u32_e32 v100, 0x3000, v235
	s_cmpk_lt_i32 s0, 0x1380
	ds_write2_b64 v100, v[96:97], v[98:99] offset0:96 offset1:100
	v_cvt_pk_bf16_f32 v96, v48, v49
	v_cvt_pk_bf16_f32 v97, v50, v51
	v_cvt_pk_bf16_f32 v98, v32, v33
	v_cvt_pk_bf16_f32 v99, v34, v35
	s_cselect_b32 s44, s7, s1
	ds_write2_b64 v100, v[96:97], v[98:99] offset0:104 offset1:108
	s_waitcnt lgkmcnt(0)
	s_barrier
	ds_read_b128 v[96:99], v218
	ds_read_b128 v[32:35], v219
	ds_read_b128 v[36:39], v220
	ds_read_b128 v[40:43], v221
	ds_read_b128 v[44:47], v222
	ds_read_b128 v[48:51], v223
	s_cselect_b32 s22, s2, 0x4000
	s_lshl_b32 s0, s44, 7
	s_ashr_i32 s1, s0, 31
	v_lshl_add_u64 v[100:101], s[0:1], 1, v[144:145]
	v_add_u32_e32 v104, s22, v205
	v_mad_i64_i32 v[102:103], s[6:7], v104, s97, v[100:101]
	s_waitcnt lgkmcnt(5)
	global_store_dwordx4 v[102:103], v[96:99], off
	v_add_u32_e32 v102, 16, v104
	v_mad_i64_i32 v[102:103], s[6:7], v102, s97, v[100:101]
	s_add_i32 s1, s44, -10
	s_waitcnt lgkmcnt(4)
	global_store_dwordx4 v[102:103], v[32:35], off
	v_add_u32_e32 v102, 32, v104
	v_mad_i64_i32 v[102:103], s[6:7], v102, s97, v[100:101]
	s_cmp_lt_u32 s1, 6
	s_waitcnt lgkmcnt(3)
	global_store_dwordx4 v[102:103], v[36:39], off
	v_add_u32_e32 v102, 48, v104
	v_mad_i64_i32 v[102:103], s[6:7], v102, s97, v[100:101]
	s_cselect_b64 s[42:43], -1, 0
	s_waitcnt lgkmcnt(2)
	global_store_dwordx4 v[102:103], v[40:43], off
	v_add_u32_e32 v102, 64, v104
	v_mad_i64_i32 v[102:103], s[6:7], v102, s97, v[100:101]
	s_cmp_gt_u32 s1, 5
	s_waitcnt lgkmcnt(1)
	global_store_dwordx4 v[102:103], v[44:47], off
	v_add_u32_e32 v102, 0x50, v104
	v_mad_i64_i32 v[102:103], s[6:7], v102, s97, v[100:101]
	s_waitcnt lgkmcnt(0)
	global_store_dwordx4 v[102:103], v[48:51], off
	ds_read_b128 v[96:99], v224
	v_add_u32_e32 v102, 0x60, v104
	v_mad_i64_i32 v[102:103], s[6:7], v102, s97, v[100:101]
	s_waitcnt lgkmcnt(0)
	global_store_dwordx4 v[102:103], v[96:99], off
	v_add_u32_e32 v102, 0x70, v104
	v_mad_i64_i32 v[100:101], s[6:7], v102, s97, v[100:101]
	s_cselect_b64 s[6:7], -1, 0
	s_sub_i32 s1, s44, 28
	s_cmp_gt_u32 s1, 9
	s_cselect_b64 s[44:45], -1, 0
	ds_read_b128 v[96:99], v225
	s_and_b64 s[6:7], s[6:7], s[44:45]
	s_cmpk_gt_i32 s22, 0x3fff
	s_cselect_b64 s[44:45], -1, 0
	s_or_b64 s[6:7], s[6:7], s[44:45]
	s_and_b64 vcc, exec, s[6:7]
	s_waitcnt lgkmcnt(0)
	global_store_dwordx4 v[100:101], v[96:99], off
	s_cbranch_vccnz .LBB0_171
; template <int MODE>
; PH void gemm_phase(const Params& p, int layer) {
;     ...
;                   const int o = tid & 15, rbase = (tid >> 4) * 8;
;                   const int nch = is_lru ? 768 : 1280;
;                   const int chn = (is_lru ? (n0 - C_XL) : (n0 - C_XBC)) + o * 8;
;                   const float* cw = (is_lru ? (p.in[11] + layer * 4 * 768) : (p.in[18] + layer * 4 * 1280)) + chn;
;                   const float* cb = (is_lru ? (p.in[12] + layer * 768) : (p.in[19] + layer * 1280)) + chn;
;                   u16* dst = (u16*)(p.ws + (is_lru ? WS_XL : WS_XBC)) + chn;
;                   float w0[8], w1[8], w2[8], w3[8], bs[8];
; #pragma unroll
;                   for (int h = 0; h < 2; ++h) {
;                     const float4 a0 = *(const float4*)(cw + 0 * nch + 4 * h), a1 = *(const float4*)(cw + 1 * nch + 4 * h);
;                     const float4 a2 = *(const float4*)(cw + 2 * nch + 4 * h), a3 = *(const float4*)(cw + 3 * nch + 4 * h);
;                     const float4 b4 = *(const float4*)(cb + 4 * h);
;                     w0[4 * h] = a0.x; w0[4 * h + 1] = a0.y; w0[4 * h + 2] = a0.z; w0[4 * h + 3] = a0.w;
;                     w1[4 * h] = a1.x; w1[4 * h + 1] = a1.y; w1[4 * h + 2] = a1.z; w1[4 * h + 3] = a1.w;
;                     w2[4 * h] = a2.x; w2[4 * h + 1] = a2.y; w2[4 * h + 2] = a2.z; w2[4 * h + 3] = a2.w;
;                     w3[4 * h] = a3.x; w3[4 * h + 1] = a3.y; w3[4 * h + 2] = a3.z; w3[4 * h + 3] = a3.w;
;                     bs[4 * h] = b4.x; bs[4 * h + 1] = b4.y; bs[4 * h + 2] = b4.z; bs[4 * h + 3] = b4.w;
;                   }
;                   float xa[8], xb[8], xc[8], xd[8], yv[8];
; #pragma unroll
;                   for (int c = 0; c < 8; ++c) { xa[c] = 0.f; xb[c] = 0.f; xc[c] = 0.f; }
;                   if (rbase >= 8) {
;                     const int r1 = rbase - 3, r2 = rbase - 2, r3 = rbase - 1;
;                     unpack8(*(const uint4*)((r1 < 64 ? eX + r1 * 136 : eW + (r1 - 64) * 136) + o * 8), xa);
;                     unpack8(*(const uint4*)((r2 < 64 ? eX + r2 * 136 : eW + (r2 - 64) * 136) + o * 8), xb);
;                     unpack8(*(const uint4*)((r3 < 64 ? eX + r3 * 136 : eW + (r3 - 64) * 136) + o * 8), xc);
;                   }
	s_and_b64 s[6:7], s[42:43], exec
	s_movk_i32 s1, 0x300
	s_cselect_b32 s44, s1, 0x500
	s_movk_i32 s1, 0xfb00
	s_cselect_b32 s1, s1, 0xfffff200
	s_add_i32 s1, s1, s0
	v_or_b32_e32 v146, s1, v206
	s_and_b64 s[0:1], s[42:43], exec
	v_ashrrev_i32_e32 v147, 31, v146
	s_cselect_b32 s1, s9, s18
	s_cselect_b32 s0, s8, s15
	v_lshlrev_b64 v[96:97], 2, v[146:147]
	v_lshl_add_u64 v[100:101], s[0:1], 0, v[96:97]
	s_cselect_b32 s1, s21, s24
	s_cselect_b32 s0, s19, s23
	s_lshl_b32 s2, s44, 2
	v_lshl_add_u64 v[104:105], v[100:101], 0, s[2:3]
	s_lshl_b32 s2, s44, 3
	v_lshl_add_u64 v[106:107], v[100:101], 0, s[2:3]
	s_mul_i32 s2, s44, 12
	v_lshl_add_u64 v[132:133], s[0:1], 0, v[96:97]
	v_lshl_add_u64 v[112:113], v[100:101], 0, s[2:3]
	global_load_dwordx4 v[96:99], v[100:101], off offset:16
	global_load_dwordx4 v[116:119], v[100:101], off
	s_nop 0
	global_load_dwordx4 v[100:103], v[104:105], off offset:16
	global_load_dwordx4 v[120:123], v[104:105], off
	global_load_dwordx4 v[108:111], v[106:107], off offset:16
	global_load_dwordx4 v[128:131], v[106:107], off
	s_nop 0
	global_load_dwordx4 v[104:107], v[112:113], off offset:16
	global_load_dwordx4 v[124:127], v[112:113], off
	s_nop 0
	global_load_dwordx4 v[112:115], v[132:133], off offset:16
	s_nop 0
	global_load_dwordx4 v[132:135], v[132:133], off
	v_mov_b32_e32 v180, 0
	v_mov_b32_e32 v181, v180
	v_mov_b32_e32 v172, v180
	v_mov_b32_e32 v173, v180
	v_mov_b32_e32 v164, v180
	v_mov_b32_e32 v165, v180
	v_mov_b32_e32 v152, v180
	v_mov_b32_e32 v153, v180
	v_mov_b32_e32 v174, v180
	v_mov_b32_e32 v175, v180
	v_mov_b32_e32 v168, v180
	v_mov_b32_e32 v169, v180
	v_mov_b32_e32 v156, v180
	v_mov_b32_e32 v157, v180
	v_mov_b32_e32 v148, v180
	v_mov_b32_e32 v149, v180
	v_mov_b32_e32 v150, v180
	v_mov_b32_e32 v151, v180
	v_mov_b32_e32 v158, v180
	v_mov_b32_e32 v159, v180
	v_mov_b32_e32 v170, v180
	v_mov_b32_e32 v171, v180
	v_mov_b32_e32 v178, v180
	v_mov_b32_e32 v179, v180
	s_and_saveexec_b64 s[0:1], s[36:37]
	s_cbranch_execz .LBB0_179
	ds_read_b128 v[136:139], v208
	ds_read_b128 v[152:155], v209
	s_waitcnt lgkmcnt(1)
	v_lshlrev_b32_e32 v178, 16, v136
	v_and_b32_e32 v179, 0xffff0000, v136
	v_lshlrev_b32_e32 v170, 16, v137
	v_and_b32_e32 v171, 0xffff0000, v137
	v_lshlrev_b32_e32 v158, 16, v138
	v_and_b32_e32 v159, 0xffff0000, v138
	v_lshlrev_b32_e32 v150, 16, v139
	v_and_b32_e32 v151, 0xffff0000, v139
	ds_read_b128 v[136:139], v210
	s_waitcnt lgkmcnt(1)
	v_lshlrev_b32_e32 v174, 16, v152
	v_and_b32_e32 v175, 0xffff0000, v152
	v_lshlrev_b32_e32 v168, 16, v153
	v_and_b32_e32 v169, 0xffff0000, v153
	v_lshlrev_b32_e32 v156, 16, v154
	v_and_b32_e32 v157, 0xffff0000, v154
	v_lshlrev_b32_e32 v148, 16, v155
	v_and_b32_e32 v149, 0xffff0000, v155
	s_waitcnt lgkmcnt(0)
	v_lshlrev_b32_e32 v180, 16, v136
	v_and_b32_e32 v181, 0xffff0000, v136
	v_lshlrev_b32_e32 v172, 16, v137
	v_and_b32_e32 v173, 0xffff0000, v137
	v_lshlrev_b32_e32 v164, 16, v138
	v_and_b32_e32 v165, 0xffff0000, v138
	v_lshlrev_b32_e32 v152, 16, v139
	v_and_b32_e32 v153, 0xffff0000, v139
